# v16 + GEMM2 residual epilogue: the four partial row sums read with four loads in flight instead of three serialised round trips
# speedup vs baseline: 1.0035x; 1.0035x over previous
.LBB0_639:
	s_waitcnt vmcnt(0) lgkmcnt(0)
	s_barrier
	s_and_saveexec_b64 s[22:23], s[4:5]
	s_cbranch_execz .LBB0_641
	global_load_dword v133, v[0:1], off sc1
	global_load_dword v134, v[0:1], off offset:4 sc1
	global_load_dword v135, v[0:1], off offset:8 sc1
	s_nop 0
	global_load_dword v0, v[0:1], off offset:12 sc1
	v_lshl_add_u32 v1, v226, 2, 16
	s_waitcnt vmcnt(3)
	v_add_f32_e32 v133, 0, v133
	s_waitcnt vmcnt(2)
	v_add_f32_e32 v133, v133, v134
	s_waitcnt vmcnt(1)
	v_add_f32_e32 v133, v133, v135
	s_waitcnt vmcnt(0)
	v_add_f32_e32 v0, v133, v0
	ds_write_b32 v1, v0 offset:4096
